# phase 4 rebalance v2: SWA+q workgroups keep one kv-up tile, the 64 odd kv-up tiles go to the two-SWA workgroups; NA bias lookups de-serialized; MLA P.V interleave
# speedup vs baseline: 1.0066x; 1.0066x over previous
; __device__ __forceinline__ int opq(int v) { asm volatile("" : "+s"(v)); return v; }
; __global__ void __launch_bounds__(NTHREADS) fwd_megakernel(Args a) {
;     ...
;             { const int bq = opq((int)blockIdx.x), Gq = opq(G);
; #pragma unroll 1
;               for (int it = 0; ; ++it) {
;                 int q0 = -1, kv0 = -1, kv1 = -1, na = -1, sw0 = -1, sw1 = -1;
;                 if (Gq == 256) { if (it == 0) {
;                     if (bq < 96) { na = bq; q0 = bq; }
;                     else if (bq < 128) { na = bq; kv0 = 2 * (bq - 96); kv1 = kv0 + 1; }
;                     else if (bq < 192) { sw0 = bq - 128; q0 = 96 + (bq - 128); kv0 = 64 + 2 * (bq - 128); kv1 = kv0 + 1; }
;                     else { sw0 = 64 + (bq - 192); sw1 = 128 + (bq - 192); } } }
;                 else { const int L = bq + it * Gq; if (L < 160) q0 = L; if (L < 192) { kv0 = L; sw0 = L; } if (L < 128) na = L; }
.LBB0_617:
	s_andn2_b64 vcc, exec, s[0:1]
	s_cbranch_vccnz .LBB0_854
	v_readlane_b32 s0, v254, 46
	v_readlane_b32 s1, v254, 47
	s_mul_i32 s1, s0, 0x5b00000
	s_lshl_b32 s0, s0, 2
	v_writelane_b32 v254, s1, 49
	v_writelane_b32 v254, s0, 50
	v_mov_b32_e32 v0, 0x80
	v_readlane_b32 s0, v254, 11
	s_mov_b32 s5, s0
	s_mov_b32 s0, s82
	v_readlane_b32 s1, v254, 12
	s_cmpk_lg_i32 s0, 0x100
	v_writelane_b32 v254, s0, 51
	s_cselect_b64 s[0:1], -1, 0
	v_writelane_b32 v254, s0, 52
	s_cmpk_gt_i32 s5, 0x5f
	v_sub_co_u32_e32 v0, vcc, s5, v0
	v_writelane_b32 v254, s1, 53
	s_cselect_b64 s[0:1], -1, 0
	v_writelane_b32 v254, s0, 54
	v_readfirstlane_b32 s2, v0
	s_lshl_b32 s4, s5, 1
	v_writelane_b32 v254, s1, 55
	v_readfirstlane_b32 s0, v0
	s_lshl_b32 s2, s2, 1
	s_add_i32 s6, s4, 0xffffff40
	v_writelane_b32 v254, s0, 56
	s_xor_b64 s[0:1], vcc, -1
	v_writelane_b32 v254, s0, 57
	s_add_i32 s3, s2, 64
	s_addk_i32 s2, 0x41
	v_writelane_b32 v254, s1, 58
	s_sub_i32 s0, s5, 64
	s_sub_i32 s1, s5, 32
	v_writelane_b32 v254, s6, 59
	s_add_i32 s6, s2, 0xffffff80
	s_addk_i32 s4, 0xff41
	v_writelane_b32 v254, s4, 60
	s_cmpk_lt_u32 s5, 0xc0
	v_writelane_b32 v254, s5, 61
	s_cselect_b32 s0, -1, s0
	v_writelane_b32 v254, s0, 62
	s_mov_b32 s0, -1
	v_writelane_b32 v254, s0, 63
	s_cselect_b32 s0, s3, s6
	v_writelane_b32 v255, s0, 0
	s_cselect_b32 s0, s1, -1
	v_writelane_b32 v255, s0, 1
	s_mov_b32 s0, 0
	v_writelane_b32 v255, s0, 2
	s_branch .LBB0_620
